# static priority raise for waves 0-3 kept for the GEMM-type phases only: priority 0 during the mLSTM scan and the attention phase
# speedup vs baseline: 1.0135x; 1.0005x over previous
; #define LAS __attribute__((address_space(3)))
; DI void scan_phase(const Args& A, LAS unsigned char* lds, int wv) {
;     const int wave = wv;
;     LAS float* wl = (LAS float*)(lds + SC_WAVE + wave * SC_WAVE_BYTES);
;     LAS unsigned* nbp = (LAS unsigned*)(lds + SC_WAVE + wave * SC_WAVE_BYTES + 2048);
;     LAS unsigned* wbp = nbp + 64;
;     LAS unsigned char* hst = lds + SC_WAVE + wave * SC_WAVE_BYTES + 2560;
;     unsigned char* ws = A.ws;
;     const bf16_t* Qg = (const bf16_t*)(ws + WS_SCR + M_Q); const bf16_t* Kg = (const bf16_t*)(ws + WS_SCR + M_K); const bf16_t* KVT = (const bf16_t*)(ws + WS_SCR + M_KVT);
;     const float* G32 = (const float*)(ws + WS_SCR + M_G32); const float* bg = A.in[10];
;     ...
;     for (int item = blockIdx.x; item < 256; item += gridDim.x) {
;         const int dir = item & 1, h = (item >> 1) & 7, b = item >> 4, e0 = wave * 32;
;         const bf16_t* Qu = Qg + (size_t)b * TB * 1024 + h * 128;
;         const bf16_t* Ku = Kg + (size_t)b * TB * 1024 + h * 128;
;         const bf16_t* KTu = KVT + ((size_t)b * 3072 + h * 128) * TB;
;         const bf16_t* VTu = KVT + ((size_t)b * 3072 + 1024 + h * 256 + e0) * TB;
;         bf16_t* Hout = (bf16_t*)(ws + WS_SCR + (dir ? M_HB : M_HF)) + (size_t)b * TB * DM + h * 256 + e0;
;         const float big = bg[(dir * 2) * 8 + h], bfg = bg[(dir * 2 + 1) * 8 + h];
.LBB0_1206:
	s_or_b64 exec, exec, s[4:5]
	s_cmpk_gt_i32 s92, 0xff
	s_waitcnt lgkmcnt(0)
	s_barrier
	s_setprio 0
	s_cbranch_scc1 .LBB0_1251
	v_writelane_b32 v247, s88, 59
	v_writelane_b32 v247, s91, 60
	v_writelane_b32 v247, s33, 61
	v_mbcnt_hi_u32_b32 v151, -1, v228
	v_readlane_b32 s1, v247, 33
	s_mul_i32 s0, s1, 0x1a00
	s_add_i32 s47, s0, 0
	s_lshl_b32 s0, s1, 5
	s_lshl_b32 s1, s1, 10
	s_add_i32 s2, s0, 0x400
	s_add_i32 s61, s1, 0
	v_writelane_b32 v247, s2, 62
	s_add_i32 s1, s61, 0x4000
	v_writelane_b32 v247, s1, 63
	s_add_i32 s1, s61, 0x8000
	v_writelane_b32 v246, s1, 0
	s_add_i32 s1, s61, 0x6000
	v_writelane_b32 v246, s1, 1
	s_add_i32 s1, s61, 0xa000
	v_writelane_b32 v246, s1, 2
	s_lshl_b32 s0, s0, 1
	v_writelane_b32 v246, s0, 3
	v_bfrev_b32_e32 v0, 0.5
	s_mov_b32 s21, 0
	s_add_i32 s47, s47, 0x18000
	s_movk_i32 s33, 0x1200
	v_mov_b32_e32 v145, 0
	s_movk_i32 s18, 0xf0
	s_add_i32 s19, s61, 0x2000
	v_mov_b32_e32 v150, 0x3ecc95a3
	v_lshl_or_b32 v152, v151, 2, v0
	s_movk_i32 s16, 0x60
	v_mov_b32_e32 v153, 0
	v_mov_b32_e32 v154, 0x7f800000
	v_mov_b32_e32 v155, 0x7fc00000
	v_mov_b32_e32 v156, 0xff800000
	v_mov_b32_e32 v157, 0xf0
	v_mov_b32_e32 v158, 0xf149f2ca
	v_mov_b32_e32 v159, 0x70
	v_writelane_b32 v246, s92, 4
	s_mov_b32 s17, s92
	s_mov_b64 s[58:59], s[96:97]
	v_writelane_b32 v246, s93, 5
	s_branch .LBB0_1209

; DI int otid(int wv) { int t; asm volatile("v_mbcnt_lo_u32_b32 %0, -1, 0\n\tv_mbcnt_hi_u32_b32 %0, -1, %0" : "=v"(t)); return wv * 64 + t; }
; DI int xcd_remap(int L, int total) { const int q = total / NXCD, r = total % NXCD, xcd = L % NXCD, off = L / NXCD; return (xcd < r ? xcd * (q + 1) : r * (q + 1) + (xcd - r) * q) + off; }
; #define PG8_WAIT_V(n) asm volatile("s_waitcnt vmcnt(" #n ")" ::: "memory")
; template <class Desc, class Epi>
; DI void gemm_phase(LAS unsigned char* lds, const Desc& D, const Epi& E, int wv) {
;     const int tid = otid(wv), wid = __builtin_amdgcn_readfirstlane(tid >> 6), lane = tid & 63, wr = wid >> 2, wc = wid & 3, fr = lane & 15, fq = lane >> 4;
;     const int G = gridDim.x, c = blockIdx.x, total = D.total;
;     const int K = D.K, nt = K / BK;
;     unsigned voffA[2], voffB[2];
; #pragma unroll
;     for (int i = 0; i < 2; ++i) { int R, C; stage_rc(tid * 16 + i * 8192, R, C); const int Rb = (R & ~31) + perm32(R & 31);
;         voffA[i] = (unsigned)(R * D.lda + C) * 2u; voffB[i] = (unsigned)(Rb * D.ldb + C) * 2u; }
;     const size_t kstep = (size_t)(BK * 2);
;     const size_t hstepA = (size_t)HALF * D.lda * 2, hstepB = (size_t)HALF * D.ldb * 2;
;     const unsigned ldsw = (unsigned)wid * 1024u;
;     const int aoff = lds_byte(wr * 64 + fr, fq * 8), boff = lds_byte(wc * 32 + fr, fq * 8);
;     ...
;     if constexpr (Desc::RAW) { if (!D.valid(c, G)) return; } else { if (c >= total) return; }
;     Unit cur, nxt; int ui = 0;
;     if constexpr (Desc::RAW) cur = D.unit(c, G); else cur = D.unit(xcd_remap(c, total));
;     nxt = cur;
;     f32x4 acc[2][2][4][2];
; #pragma unroll
;     for (int a = 0; a < 2; ++a)
; #pragma unroll
;         for (int b = 0; b < 2; ++b)
; #pragma unroll
;             for (int m = 0; m < 4; ++m)
; #pragma unroll
;                 for (int n = 0; n < 2; ++n) acc[a][b][m][n] = (f32x4){0.f, 0.f, 0.f, 0.f};
;     bf16x8 At[4][2], B0[2][2], B1[2][2];
;     const char* cA = cur.a; const char* cB = cur.b;
;     PG8_STAGE(PG8_SB(0, 0), cB, voffB); PG8_STAGE(PG8_SB(0, 1), cB + hstepB, voffB); PG8_STAGE(PG8_SA(0, 0), cA, voffA); PG8_STAGE(PG8_SA(0, 1), cA + hstepA, voffA);
;     if (wr == 1) PG8_BAR;
;     PG8_WAIT_V(2); PG8_BAR;
;     PG8_STAGE(PG8_SB(1, 0), cB + kstep, voffB); PG8_STAGE(PG8_SA(1, 0), cA + kstep, voffA); PG8_STAGE(PG8_SB(1, 1), cB + hstepB + kstep, voffB);
;     PG8_WAIT_V(6); PG8_BAR;
.LBB0_1304:
	s_or_b64 exec, exec, s[4:5]
	s_waitcnt lgkmcnt(0)
	s_barrier
	s_cselect_b32 s98, 1, 0
	s_cmp_lt_u32 s90, 0x100
	s_cbranch_scc0 .Lprio_skip_8
	s_setprio 1
.Lprio_skip_8:
	s_cmp_lg_u32 s98, 0
	v_mbcnt_lo_u32_b32 v9, -1, 0
	v_mbcnt_hi_u32_b32 v9, -1, v9
	s_cmpk_gt_i32 s92, 0x8ff
	v_add_u32_e32 v0, s90, v9
	s_nop 0
	v_readfirstlane_b32 s5, v0
	s_cbranch_scc1 .LBB0_1384
	v_lshlrev_b32_e32 v1, 4, v0
	v_add_u32_e32 v2, 0x2000, v1
	v_ashrrev_i32_e32 v3, 31, v2
	v_lshrrev_b32_e32 v3, 22, v3
	v_add_u32_e32 v3, v2, v3
	v_ashrrev_i32_e32 v8, 10, v3
	v_mul_i32_i24_e32 v3, 0x400, v8
	v_sub_u32_e32 v2, v2, v3
	v_lshrrev_b32_e32 v3, 4, v2
	v_bitop3_b32 v2, v3, v2, 32 bitop3:0x6c
	v_ashrrev_i32_e32 v3, 31, v2
	v_lshrrev_b32_e32 v3, 26, v3
	v_add_u32_e32 v3, v2, v3
	v_lshlrev_b32_e32 v4, 3, v8
	v_ashrrev_i32_e32 v10, 6, v3
	v_and_b32_e32 v4, -16, v4
	v_add_u32_e32 v4, v10, v4
	v_and_b32_e32 v5, 3, v10
	s_mov_b32 s3, 0xfffe0
	v_lshrrev_b32_e32 v6, 2, v4
	v_lshlrev_b32_e32 v7, 1, v4
	v_and_b32_e32 v3, 0xc0, v3
	v_and_or_b32 v5, v4, s3, v5
	v_and_b32_e32 v6, 4, v6
	v_and_b32_e32 v7, 24, v7
	v_sub_u32_e32 v2, v2, v3
	v_mov_b32_e32 v3, 1
	v_or3_b32 v5, v5, v6, v7
	v_lshlrev_b32_e32 v6, 5, v8
	v_ashrrev_i16_sdwa v2, v3, sext(v2) dst_sel:DWORD dst_unused:UNUSED_PAD src0_sel:DWORD src1_sel:BYTE_0
	v_and_b32_e32 v6, 32, v6
	v_bfe_i32 v11, v2, 0, 16
	v_add_lshl_u32 v2, v6, v11, 1
	v_lshl_add_u32 v128, v5, 12, v2
	v_lshl_add_u32 v130, v4, 12, v2
	v_bfe_i32 v2, v0, 27, 1
	v_lshrrev_b32_e32 v2, 22, v2
	v_add_u32_e32 v2, v1, v2
	v_and_b32_e32 v2, 0xfffffc00, v2
	v_sub_u32_e32 v1, v1, v2
	v_lshrrev_b32_e32 v2, 4, v1
	v_ashrrev_i32_e32 v4, 31, v0
	v_bitop3_b32 v1, v2, v1, 32 bitop3:0x6c
	v_lshrrev_b32_e32 v4, 26, v4
	v_ashrrev_i32_e32 v2, 31, v1
	v_add_u32_e32 v0, v0, v4
	v_lshrrev_b32_e32 v2, 26, v2
	v_ashrrev_i32_e32 v13, 6, v0
	v_add_u32_e32 v2, v1, v2
	v_lshlrev_b32_e32 v0, 3, v13
	v_ashrrev_i32_e32 v12, 6, v2
	v_and_b32_e32 v0, -16, v0
	s_add_u32 s0, s58, 0x2b00000
	v_add_u32_e32 v0, v12, v0
	v_and_b32_e32 v4, 3, v12
	s_addc_u32 s1, s59, 0
	v_and_or_b32 v4, v0, s3, v4
	s_lshr_b32 s3, s89, 29
	s_add_i32 s4, s92, s3
	s_ashr_i32 s10, s5, 6
	s_and_b32 s3, s4, -8
	s_ashr_i32 s11, s5, 8
	s_lshl_b32 s2, s10, 10
	s_sub_i32 s6, s92, s3
	s_cmp_lt_i32 s6, 0
	s_movk_i32 s3, 0x121
	s_cselect_b32 s7, s3, 0x120
	s_mul_i32 s6, s7, s6
	s_ashr_i32 s4, s4, 3
	s_add_i32 s4, s6, s4
	s_ashr_i32 s6, s4, 31
	s_lshr_b32 s6, s6, 25
	s_add_i32 s6, s4, s6
	s_ashr_i32 s7, s6, 7
	s_and_b32 s6, s6, 0xffffff80
	s_sub_i32 s6, s4, s6
	s_bfe_i32 s4, s6, 0x80000
	s_bfe_u32 s4, s4, 0x3000c
	s_add_i32 s8, s6, s4
	s_bfe_i32 s4, s8, 0x80000
	s_and_b32 s8, s8, 0xf8
	s_sub_i32 s6, s6, s8
	s_lshl_b32 s7, s7, 3
	s_sext_i32_i16 s4, s4
	s_sext_i32_i8 s6, s6
	v_lshrrev_b32_e32 v5, 2, v0
	v_lshlrev_b32_e32 v6, 1, v0
	v_and_b32_e32 v2, 0xc0, v2
	s_lshr_b32 s4, s4, 3
	s_add_i32 s6, s7, s6
	v_and_b32_e32 v5, 4, v5
	v_and_b32_e32 v6, 24, v6
	v_sub_u32_e32 v1, v1, v2
	s_ashr_i32 s7, s6, 31
	s_bfe_i64 s[12:13], s[4:5], 0x100000
	v_or3_b32 v4, v4, v5, v6
	v_lshlrev_b32_e32 v5, 5, v13
	v_ashrrev_i16_sdwa v1, v3, sext(v1) dst_sel:DWORD dst_unused:UNUSED_PAD src0_sel:DWORD src1_sel:BYTE_0
	s_lshl_b64 s[8:9], s[6:7], 20
	s_lshl_b64 s[12:13], s[12:13], 20
	v_and_b32_e32 v5, 32, v5
	v_bfe_i32 v14, v1, 0, 16
	s_add_u32 s40, s0, s12
	v_add_lshl_u32 v1, v5, v14, 1
	s_addc_u32 s41, s1, s13
	s_add_i32 s28, s2, 0
	v_lshl_add_u32 v132, v4, 12, v1
	s_add_i32 m0, s28, 0x10000
	v_lshl_add_u32 v134, v0, 12, v1
	global_load_lds_dwordx4 v132, s[40:41]
	s_add_i32 m0, s28, 0x12000
	s_add_u32 s12, s40, 0x80000
	global_load_lds_dwordx4 v128, s[40:41]
	s_addc_u32 s13, s41, 0
	s_add_i32 m0, s28, 0x14000
	v_mov_b32_e32 v137, 0
	global_load_lds_dwordx4 v132, s[12:13]
	s_add_i32 m0, s28, 0x16000
	s_add_u32 s22, s36, s8
	s_addc_u32 s23, s37, s9
	s_add_i32 s29, s28, 0x2000
	global_load_lds_dwordx4 v128, s[12:13]
	s_mov_b32 m0, s28
	s_add_u32 s8, s22, 0x80000
	global_load_lds_dwordx4 v134, s[22:23]
	s_mov_b32 m0, s29
	s_addc_u32 s9, s23, 0
	s_add_i32 s30, s28, 0x4000
	global_load_lds_dwordx4 v130, s[22:23]
	s_mov_b32 m0, s30
	s_add_i32 s31, s28, 0x6000
	global_load_lds_dwordx4 v134, s[8:9]
	s_mov_b32 m0, s31
	v_mov_b32_e32 v133, v137
	global_load_lds_dwordx4 v130, s[8:9]
	v_mov_b32_e32 v129, v137
	v_mov_b32_e32 v135, v137
	v_mov_b32_e32 v131, v137
	s_cmp_eq_u32 s11, 1
	s_mov_b32 s34, 0
	v_lshl_add_u64 v[6:7], s[40:41], 0, v[132:133]
	v_lshl_add_u64 v[4:5], s[40:41], 0, v[128:129]
	v_lshl_add_u64 v[0:1], s[22:23], 0, v[134:135]
	s_cselect_b64 s[8:9], -1, 0
	s_cmp_lg_u32 s11, 1
	v_lshl_add_u64 v[2:3], s[22:23], 0, v[130:131]
	s_cbranch_scc1 .LBB0_1307
	s_barrier

; DI int otid(int wv) { int t; asm volatile("v_mbcnt_lo_u32_b32 %0, -1, 0\n\tv_mbcnt_hi_u32_b32 %0, -1, %0" : "=v"(t)); return wv * 64 + t; }
; DI void attn_layer(const Args& A, LAS unsigned char* lds, char* lds_gen, const XcdBarrier& gbar, int layer, int wv) {
;     ...
;     {
;         const int G = gridDim.x, c = blockIdx.x;
;         { f32x2* rope = (f32x2*)(lds_gen + 81920); const int tid = otid(wv);
;           for (int e = tid; e < 2048; e += NTHREADS) { const float ang = (float)(e >> 5) * exp2f(-(float)(e & 31) * 0.41524101186092029f); rope[e] = (f32x2){cosf(ang), sinf(ang)}; }
;           __syncthreads(); }
.LBB0_1958:
	s_or_b64 exec, exec, s[0:1]
	s_waitcnt lgkmcnt(0)
	s_barrier
	s_setprio 0
	v_mbcnt_lo_u32_b32 v0, -1, 0
	v_mbcnt_hi_u32_b32 v0, -1, v0
	s_movk_i32 s0, 0x800
	v_add_u32_e32 v2, s90, v0
	v_cmp_gt_i32_e32 vcc, s0, v2
	s_and_saveexec_b64 s[8:9], vcc
	s_cbranch_execz .LBB0_1969
	v_and_b32_e32 v1, 31, v0
	v_cvt_f32_ubyte0_e32 v1, v1
	v_mul_f32_e32 v3, 0xbed49a78, v1
	s_mov_b32 s0, 0xc2fc0000
	v_mov_b32_e32 v4, 0x42800000
	v_cmp_gt_f32_e32 vcc, s0, v3
	v_readlane_b32 s0, v247, 33
	s_lshl_b32 s0, s0, 9
	v_cndmask_b32_e32 v3, 0, v4, vcc
	v_fmac_f32_e32 v3, 0xbed49a78, v1
	v_exp_f32_e32 v1, v3
	v_not_b32_e32 v3, 63
	s_add_i32 s0, s0, 0
	v_cndmask_b32_e32 v4, 0, v3, vcc
	v_lshl_add_u32 v0, v0, 3, s0
	v_ldexp_f32 v4, v1, v4
	v_add_u32_e32 v5, 0x14000, v0
	s_mov_b64 s[10:11], 0
	s_brev_b32 s2, 18
	s_mov_b32 s3, 0xfe5163ab
	v_mov_b32_e32 v1, 0
	s_mov_b32 s16, 0x3c439041
	s_mov_b32 s17, 0xdb629599
	s_mov_b32 s18, 0xf534ddc0
	s_mov_b32 s19, 0xfc2757d1
	s_mov_b32 s20, 0x4e441529
	s_mov_b32 s21, 0xa2f9836e
	s_mov_b32 s22, 0x3fc90fda
	s_mov_b32 s23, 0x3f22f983
	s_mov_b32 s28, 0xbfc90fda
	v_mov_b32_e32 v6, 0x3c0881c4
	v_mov_b32_e32 v7, 0xbab64f3b
	s_brev_b32 s29, 1
	s_movk_i32 s30, 0x1f8
	s_movk_i32 s31, 0x5ff
	v_not_b32_e32 v8, 31
	v_mov_b32_e32 v9, 0x7fc00000
	s_branch .LBB0_1961

; DI void attn_layer(const Args& A, LAS unsigned char* lds, char* lds_gen, const XcdBarrier& gbar, int layer, int wv) {
;     ...
;     {
;         DescPlain D; D.init(U, (const bf16_t*)(ws + WS_WAO), 8, true);
;         EpiResid E; E.init(A, layer);
;         pg8::gemm_phase(lds, D, E, wv);
.LBB0_2071:
	s_or_b64 exec, exec, s[0:1]
	s_waitcnt lgkmcnt(0)
	s_barrier
	s_cselect_b32 s98, 1, 0
	s_cmp_lt_u32 s90, 0x100
	s_cbranch_scc0 .Lprio_skip_15
	s_setprio 1
.Lprio_skip_15:
	s_cmp_lg_u32 s98, 0
	v_mbcnt_lo_u32_b32 v8, -1, 0
	v_mbcnt_hi_u32_b32 v8, -1, v8
	s_cmpk_lt_i32 s92, 0x400
	v_add_u32_e32 v0, s90, v8
	s_cselect_b64 s[4:5], -1, 0
	s_cmpk_gt_i32 s92, 0x3ff
	v_readfirstlane_b32 s10, v0
	s_cbranch_scc1 .LBB0_2095
	s_lshr_b32 s0, s89, 29
	s_add_i32 s6, s92, s0
	s_and_b32 s0, s6, -8
	s_sub_i32 s2, s92, s0
	s_cmp_gt_i32 s2, -1
	s_cbranch_scc0 .LBB0_2074
	s_lshl_b32 s7, s2, 7
	s_cbranch_execz .LBB0_2075
	s_branch .LBB0_2076
